# GLA scan: per-block output produced transposed (o-chain MFMA operands swapped) and stored as 4 dwordx2 per wave instead of 16 short stores; loop-head wait made explicit (vmcnt(4))
# speedup vs baseline: 1.0149x; 1.0007x over previous
.LBB0_243:
	s_or_b64 exec, exec, s[10:11]
	s_add_i32 s10, 0, 0x19800
	s_cmpk_lg_i32 s26, 0x7f3
	s_cselect_b32 s11, s24, 31
	s_add_i32 s28, s11, s6
	s_ashr_i32 s29, s28, 31
	s_lshl_b64 s[52:53], s[28:29], 15
	v_lshlrev_b32_e32 v8, 1, v108
	s_add_u32 s54, s13, s52
	v_and_b32_e32 v8, 0x7e, v8
	v_ashrrev_i32_e32 v9, 2, v108
	s_addc_u32 s55, s14, s53
	s_waitcnt vmcnt(6)
	v_lshlrev_b32_e32 v0, 16, v131
	s_waitcnt vmcnt(4)
	v_lshlrev_b32_e32 v1, 16, v133
	s_waitcnt vmcnt(2)
	v_lshlrev_b32_e32 v2, 16, v135
	s_waitcnt vmcnt(0)
	v_lshlrev_b32_e32 v3, 16, v137
	v_lshrrev_b32_e32 v4, 16, v130
	v_lshrrev_b32_e32 v5, 16, v132
	v_mul_u32_u24_e32 v8, 0x90, v8
	v_and_b32_e32 v9, -16, v9
	v_lshlrev_b32_e32 v208, 1, v108
	v_and_b32_e32 v208, 14, v208
	v_add_u32_e32 v208, 4, v208
	v_lshlrev_b32_e32 v208, 1, v208
	v_and_b32_e32 v208, 16, v208
	v_xor_b32_e32 v9, v9, v208
	s_add_u32 s52, s15, s52
	v_add_u32_e32 v12, 0x2000, v106
	v_add_u32_e32 v20, 0x4000, v106
	v_add_u32_e32 v28, 0x6000, v106
	v_and_or_b32 v0, v130, s35, v0
	v_and_or_b32 v1, v132, s35, v1
	v_and_or_b32 v2, v134, s35, v2
	v_and_or_b32 v3, v136, s35, v3
	v_and_or_b32 v4, v131, s88, v4
	v_and_or_b32 v5, v133, s88, v5
	v_lshrrev_b32_e32 v6, 16, v134
	v_lshrrev_b32_e32 v7, 16, v136
	v_add3_u32 v8, s10, v8, v9
	s_addc_u32 s53, s16, s53
	v_ashrrev_i32_e32 v13, 31, v12
	v_ashrrev_i32_e32 v21, 31, v20
	v_ashrrev_i32_e32 v29, 31, v28
	v_and_or_b32 v6, v135, s88, v6
	v_and_or_b32 v7, v137, s88, v7
	ds_write_b128 v8, v[0:3]
	ds_write_b128 v8, v[4:7] offset:144
	v_lshl_add_u64 v[4:5], s[52:53], 0, v[106:107]
	v_lshl_add_u64 v[8:9], s[54:55], 0, v[12:13]
	v_lshl_add_u64 v[12:13], s[52:53], 0, v[12:13]
	v_lshl_add_u64 v[16:17], s[54:55], 0, v[20:21]
	v_lshl_add_u64 v[20:21], s[52:53], 0, v[20:21]
	v_lshl_add_u64 v[24:25], s[54:55], 0, v[28:29]
	v_lshl_add_u64 v[28:29], s[52:53], 0, v[28:29]
	s_lshl_b64 s[52:53], s[28:29], 13
	s_add_u32 s52, s17, s52
	s_addc_u32 s53, s18, s53
	s_lshl_b64 s[28:29], s[28:29], 11
	s_add_u32 s28, s19, s28
	v_lshl_add_u64 v[0:1], s[54:55], 0, v[106:107]
	v_lshl_add_u64 v[32:33], s[52:53], 0, v[106:107]
	s_addc_u32 s29, s20, s29
	v_and_b32_e32 v106, 63, v108
	s_lshl_b32 s11, s11, 6
	s_waitcnt lgkmcnt(0)
	s_barrier
	v_lshlrev_b32_e32 v40, 4, v106
	s_sub_i32 s47, 0x7ff, s11
	global_load_dwordx4 v[0:3], v[0:1], off
	v_and_b32_e32 v107, -8, v64
	global_load_dwordx4 v[40:43], v40, s[28:29]
	s_and_b64 s[28:29], vcc, exec
	s_cselect_b32 s11, s11, s47
	s_add_i32 s11, s11, s7
	s_mul_hi_i32 s29, s11, 0xa080
	s_mul_i32 s11, s11, 0xa080
	v_lshl_or_b32 v106, v106, 1, s23
	s_add_u32 s28, s0, s11
	v_mad_u64_u32 v[108:109], s[52:53], v107, s22, v[106:107]
	s_addc_u32 s29, s2, s29
	v_ashrrev_i32_e32 v109, 31, v108
	v_lshl_add_u64 v[110:111], v[108:109], 1, s[28:29]
	v_add_u32_e32 v108, s22, v108
	v_ashrrev_i32_e32 v109, 31, v108
	global_load_dword v130, v[110:111], off
	v_lshl_add_u64 v[110:111], v[108:109], 1, s[28:29]
	v_add_u32_e32 v108, s22, v108
	v_ashrrev_i32_e32 v109, 31, v108
	global_load_dword v131, v[110:111], off
	v_lshl_add_u64 v[110:111], v[108:109], 1, s[28:29]
	v_add_u32_e32 v108, s22, v108
	v_ashrrev_i32_e32 v109, 31, v108
	global_load_dword v132, v[110:111], off
	v_lshl_add_u64 v[110:111], v[108:109], 1, s[28:29]
	v_add_u32_e32 v108, s22, v108
	v_ashrrev_i32_e32 v109, 31, v108
	global_load_dword v133, v[110:111], off
	v_lshl_add_u64 v[110:111], v[108:109], 1, s[28:29]
	v_add_u32_e32 v108, s22, v108
	v_ashrrev_i32_e32 v109, 31, v108
	v_or_b32_e32 v64, 7, v64
	global_load_dword v134, v[110:111], off
	v_lshl_add_u64 v[110:111], v[108:109], 1, s[28:29]
	v_add_u32_e32 v108, s22, v108
	v_mad_u64_u32 v[106:107], s[52:53], v64, s22, v[106:107]
	v_ashrrev_i32_e32 v109, 31, v108
	v_ashrrev_i32_e32 v107, 31, v106
	v_lshl_add_u64 v[108:109], v[108:109], 1, s[28:29]
	v_lshl_add_u64 v[106:107], v[106:107], 1, s[28:29]
	global_load_dwordx4 v[4:7], v[4:5], off
	s_nop 0
	global_load_dwordx4 v[8:11], v[8:9], off
	s_nop 0
	global_load_dwordx4 v[12:15], v[12:13], off
	s_nop 0
	global_load_dwordx4 v[16:19], v[16:17], off
	s_nop 0
	global_load_dwordx4 v[20:23], v[20:21], off
	s_nop 0
	global_load_dwordx4 v[24:27], v[24:25], off
	s_nop 0
	global_load_dwordx4 v[28:31], v[28:29], off
	s_nop 0
	global_load_dwordx4 v[32:35], v[32:33], off
	s_nop 0
	global_load_dword v135, v[110:111], off
	global_load_dword v136, v[108:109], off
	global_load_dword v137, v[106:107], off
	v_mov_b32_e32 v64, 0
	s_cmp_lg_u32 s36, -1
	v_add_u32_e32 v106, v64, v189
	v_and_b32_e32 v64, 15, v106
	v_ashrrev_i32_e32 v140, 4, v106
	v_and_b32_e32 v106, -16, v106
	v_add_u32_e32 v208, 4, v64
	v_lshlrev_b32_e32 v208, 1, v208
	v_and_b32_e32 v208, 16, v208
	v_xor_b32_e32 v208, v106, v208
	s_cselect_b32 s11, s36, 0
	s_cmp_lg_u32 s10, -1
	v_mad_u32_u24 v109, v64, s38, v208
	s_cselect_b32 s10, s10, 0
	s_cmp_lg_u32 0, -1
	v_mul_u32_u24_e32 v107, 0x210, v64
	v_lshlrev_b32_e32 v108, 3, v140
	v_add_u32_e32 v138, s11, v109
	s_cselect_b32 s11, 0, 0
	s_cmp_lg_u32 s27, -1
	v_add3_u32 v128, v107, s11, v108
	s_cselect_b32 s11, s27, 0
	v_add_u32_e32 v114, s11, v109
	s_add_i32 s11, 0, 0x22400
	v_or_b32_e32 v110, s4, v64
	s_cmp_lg_u32 s11, -1
	s_cselect_b32 s11, s11, 0
	v_mul_lo_u32 v107, v110, s38
	v_add_u32_e32 v139, s11, v106
	v_add3_u32 v115, v208, s10, v107
	ds_read_b64 v[106:107], v128 offset:0
	ds_read_b64 v[108:109], v128 offset:32
	ds_read_b64 v[110:111], v128 offset:0x2100
	ds_read_b64 v[112:113], v128 offset:0x2120
	ds_read_b64 v[116:117], v128 offset:0x4200
	ds_read_b64 v[118:119], v128 offset:0x4220
	ds_read_b64 v[120:121], v128 offset:0x6300
	ds_read_b64 v[122:123], v128 offset:0x6320
	ds_read_b64 v[124:125], v128 offset:64
	ds_read_b64 v[126:127], v128 offset:0x60
	ds_read_b64 v[142:143], v128 offset:0x2140
	ds_read_b64 v[144:145], v128 offset:0x2160
	ds_read_b64 v[154:155], v128 offset:0x4240
	ds_read_b64 v[156:157], v128 offset:0x4260
	ds_read_b64 v[158:159], v128 offset:0x6340
	ds_read_b64 v[160:161], v128 offset:0x6360
	s_waitcnt lgkmcnt(0)
	v_cvt_pk_bf16_f32 v162, v102, v103
	v_cvt_pk_bf16_f32 v163, v104, v105
	v_cvt_pk_bf16_f32 v164, v98, v99
	v_cvt_pk_bf16_f32 v165, v100, v101
	v_cvt_pk_bf16_f32 v166, v94, v95
	v_cvt_pk_bf16_f32 v167, v96, v97
	v_cvt_pk_bf16_f32 v168, v90, v91
	v_cvt_pk_bf16_f32 v169, v92, v93
	v_mfma_f32_16x16x32_bf16 v[106:109], v[162:165], v[106:109], 0
	v_cvt_pk_bf16_f32 v178, v74, v75
	v_cvt_pk_bf16_f32 v179, v76, v77
	v_cvt_pk_bf16_f32 v180, v66, v67
	v_mfma_f32_16x16x32_bf16 v[110:113], v[162:165], v[110:113], 0
	v_cvt_pk_bf16_f32 v181, v68, v69
	v_cvt_pk_bf16_f32 v192, v60, v61
	v_cvt_pk_bf16_f32 v193, v62, v63
	v_mfma_f32_16x16x32_bf16 v[116:119], v[162:165], v[116:119], 0
	v_cvt_pk_bf16_f32 v194, v56, v57
	v_cvt_pk_bf16_f32 v195, v58, v59
	v_mfma_f32_16x16x32_bf16 v[106:109], v[166:169], v[124:127], v[106:109]
	ds_read_b64 v[124:125], v128 offset:0x80
	ds_read_b64 v[126:127], v128 offset:0xa0
	v_mfma_f32_16x16x32_bf16 v[120:123], v[162:165], v[120:123], 0
	v_mfma_f32_16x16x32_bf16 v[110:113], v[166:169], v[142:145], v[110:113]
	ds_read_b64 v[142:143], v128 offset:0x2180
	ds_read_b64 v[144:145], v128 offset:0x21a0
	v_mfma_f32_16x16x32_bf16 v[116:119], v[166:169], v[154:157], v[116:119]
	ds_read_b64 v[154:155], v128 offset:0x4280
	ds_read_b64 v[156:157], v128 offset:0x42a0
	v_mfma_f32_16x16x32_bf16 v[120:123], v[166:169], v[158:161], v[120:123]
	ds_read_b64 v[158:159], v128 offset:0x6380
	ds_read_b64 v[160:161], v128 offset:0x63a0
	ds_read_b64 v[162:163], v128 offset:0xc0
	ds_read_b64 v[164:165], v128 offset:0xe0
	ds_read_b64 v[166:167], v128 offset:0x21c0
	ds_read_b64 v[168:169], v128 offset:0x21e0
	ds_read_b64 v[170:171], v128 offset:0x42c0
	ds_read_b64 v[172:173], v128 offset:0x42e0
	ds_read_b64 v[174:175], v128 offset:0x63c0
	ds_read_b64 v[176:177], v128 offset:0x63e0
	s_waitcnt lgkmcnt(0)
	v_mfma_f32_16x16x32_bf16 v[106:109], v[178:181], v[124:127], v[106:109]
	ds_read_b64 v[124:125], v128 offset:0x100
	ds_read_b64 v[126:127], v128 offset:0x120
	v_mfma_f32_16x16x32_bf16 v[110:113], v[178:181], v[142:145], v[110:113]
	ds_read_b64 v[142:143], v128 offset:0x2200
	ds_read_b64 v[144:145], v128 offset:0x2220
	v_mfma_f32_16x16x32_bf16 v[116:119], v[178:181], v[154:157], v[116:119]
	ds_read_b64 v[154:155], v128 offset:0x4300
	ds_read_b64 v[156:157], v128 offset:0x4320
	v_mfma_f32_16x16x32_bf16 v[120:123], v[178:181], v[158:161], v[120:123]
	ds_read_b64 v[158:159], v128 offset:0x6400
	ds_read_b64 v[160:161], v128 offset:0x6420
	v_cvt_pk_bf16_f32 v178, v86, v87
	v_mfma_f32_16x16x32_bf16 v[106:109], v[192:195], v[162:165], v[106:109]
	ds_read_b64 v[162:163], v128 offset:0x140
	ds_read_b64 v[164:165], v128 offset:0x160
	v_cvt_pk_bf16_f32 v179, v88, v89
	v_mfma_f32_16x16x32_bf16 v[110:113], v[192:195], v[166:169], v[110:113]
	ds_read_b64 v[166:167], v128 offset:0x2240
	ds_read_b64 v[168:169], v128 offset:0x2260
	v_cvt_pk_bf16_f32 v180, v82, v83
	v_mfma_f32_16x16x32_bf16 v[116:119], v[192:195], v[170:173], v[116:119]
	ds_read_b64 v[170:171], v128 offset:0x4340
	ds_read_b64 v[172:173], v128 offset:0x4360
	v_cvt_pk_bf16_f32 v181, v84, v85
	v_mfma_f32_16x16x32_bf16 v[120:123], v[192:195], v[174:177], v[120:123]
	ds_read_b64 v[174:175], v128 offset:0x6440
	ds_read_b64 v[176:177], v128 offset:0x6460
	s_waitcnt lgkmcnt(0)
	v_cvt_pk_bf16_f32 v192, v78, v79
	v_cvt_pk_bf16_f32 v193, v80, v81
	v_cvt_pk_bf16_f32 v194, v70, v71
	v_cvt_pk_bf16_f32 v195, v72, v73
	v_mfma_f32_16x16x32_bf16 v[106:109], v[178:181], v[124:127], v[106:109]
	ds_read_b64 v[124:125], v128 offset:0x180
	ds_read_b64 v[126:127], v128 offset:0x1a0
	v_mfma_f32_16x16x32_bf16 v[110:113], v[178:181], v[142:145], v[110:113]
	ds_read_b64 v[142:143], v128 offset:0x2280
	ds_read_b64 v[144:145], v128 offset:0x22a0
	v_mfma_f32_16x16x32_bf16 v[116:119], v[178:181], v[154:157], v[116:119]
	ds_read_b64 v[154:155], v128 offset:0x4380
	ds_read_b64 v[156:157], v128 offset:0x43a0
	v_mfma_f32_16x16x32_bf16 v[120:123], v[178:181], v[158:161], v[120:123]
	ds_read_b64 v[158:159], v128 offset:0x6480
	ds_read_b64 v[160:161], v128 offset:0x64a0
	v_cvt_pk_bf16_f32 v178, v48, v49
	v_mfma_f32_16x16x32_bf16 v[106:109], v[192:195], v[162:165], v[106:109]
	ds_read_b64 v[162:163], v128 offset:0x1c0
	ds_read_b64 v[164:165], v128 offset:0x1e0
	v_cvt_pk_bf16_f32 v179, v50, v51
	v_mfma_f32_16x16x32_bf16 v[110:113], v[192:195], v[166:169], v[110:113]
	ds_read_b64 v[166:167], v128 offset:0x22c0
	ds_read_b64 v[168:169], v128 offset:0x22e0
	v_cvt_pk_bf16_f32 v180, v44, v45
	v_mfma_f32_16x16x32_bf16 v[116:119], v[192:195], v[170:173], v[116:119]
	ds_read_b64 v[170:171], v128 offset:0x43c0
	ds_read_b64 v[172:173], v128 offset:0x43e0
	v_cvt_pk_bf16_f32 v181, v46, v47
	v_mfma_f32_16x16x32_bf16 v[120:123], v[192:195], v[174:177], v[120:123]
	ds_read_b64 v[174:175], v128 offset:0x64c0
	ds_read_b64 v[176:177], v128 offset:0x64e0
	s_waitcnt lgkmcnt(0)
	v_cvt_pk_bf16_f32 v192, v36, v37
	v_cvt_pk_bf16_f32 v193, v38, v39
	v_cvt_pk_bf16_f32 v194, v52, v53
	v_cvt_pk_bf16_f32 v195, v54, v55
	v_mfma_f32_16x16x32_bf16 v[110:113], v[178:181], v[142:145], v[110:113]
	v_mfma_f32_16x16x32_bf16 v[106:109], v[178:181], v[124:127], v[106:109]
	v_mfma_f32_16x16x32_bf16 v[142:145], v[192:195], v[166:169], v[110:113]
	ds_read_b128 v[110:113], v115 offset:0
	v_mfma_f32_16x16x32_bf16 v[124:127], v[192:195], v[162:165], v[106:109]
	ds_read_b128 v[106:109], v115 offset:64
	v_mfma_f32_16x16x32_bf16 v[116:119], v[178:181], v[154:157], v[116:119]
	ds_read_b128 v[154:157], v114 offset:0
	v_mfma_f32_16x16x32_bf16 v[120:123], v[178:181], v[158:161], v[120:123]
	ds_read_b128 v[158:161], v114 offset:64
	ds_read_b128 v[162:165], v114 offset:0x900
	ds_read_b128 v[166:169], v114 offset:0x940
	v_mfma_f32_16x16x32_bf16 v[116:119], v[192:195], v[170:173], v[116:119]
	ds_read_b128 v[170:173], v114 offset:0x1200
	v_mfma_f32_16x16x32_bf16 v[120:123], v[192:195], v[174:177], v[120:123]
	ds_read_b128 v[174:177], v114 offset:0x1240
	ds_read_b128 v[178:181], v114 offset:0x1b00
	ds_read_b128 v[192:195], v114 offset:0x1b40
	s_waitcnt lgkmcnt(0)
	s_nop 0
	v_mfma_f32_16x16x32_bf16 v[124:127], v[110:113], v[154:157], v[124:127]
	v_mfma_f32_16x16x32_bf16 v[142:145], v[110:113], v[162:165], v[142:145]
	v_mfma_f32_16x16x32_bf16 v[114:117], v[110:113], v[170:173], v[116:119]
	v_mfma_f32_16x16x32_bf16 v[154:157], v[110:113], v[178:181], v[120:123]
	v_mfma_f32_16x16x32_bf16 v[126:129], v[106:109], v[158:161], v[124:127]
	v_mfma_f32_16x16x32_bf16 v[122:125], v[106:109], v[166:169], v[142:145]
	ds_read_b128 v[142:145], v138 offset:0
	v_mfma_f32_16x16x32_bf16 v[118:121], v[106:109], v[174:177], v[114:117]
	v_mfma_f32_16x16x32_bf16 v[114:117], v[106:109], v[192:195], v[154:157]
	ds_read_b128 v[154:157], v138 offset:64
	ds_read_b128 v[158:161], v138 offset:0x900
	ds_read_b128 v[162:165], v138 offset:0x940
	ds_read_b128 v[166:169], v138 offset:0x1200
	ds_read_b128 v[170:173], v138 offset:0x1240
	ds_read_b128 v[174:177], v138 offset:0x1b00
	ds_read_b128 v[178:181], v138 offset:0x1b40
	ds_read_b128 v[192:195], v139 offset:0
	ds_read_b128 v[196:199], v139 offset:64
	ds_read_b128 v[200:203], v139 offset:0x80
	ds_read_b128 v[204:207], v139 offset:0xc0
	s_waitcnt lgkmcnt(0)
	s_nop 0
	v_mul_f32_e64 v104, v104, v194
	v_mul_f32_e64 v105, v105, v195
	v_pk_mul_f32 v[102:103], v[102:103], v[192:193]
	v_pk_mul_f32 v[100:101], v[100:101], v[198:199]
	v_pk_mul_f32 v[98:99], v[98:99], v[196:197]
	v_mfma_f32_16x16x32_bf16 v[102:105], v[142:145], v[110:113], v[102:105]
	v_mul_f32_e64 v96, v96, v202
	v_mul_f32_e64 v97, v97, v203
	v_pk_mul_f32 v[94:95], v[94:95], v[200:201]
	ds_read_b128 v[142:145], v138 offset:0x2400
	v_mfma_f32_16x16x32_bf16 v[98:101], v[158:161], v[110:113], v[98:101]
	v_mul_f32_e64 v92, v92, v206
	v_mul_f32_e64 v93, v93, v207
	v_pk_mul_f32 v[90:91], v[90:91], v[204:205]
	v_mfma_f32_16x16x32_bf16 v[94:97], v[166:169], v[110:113], v[94:97]
	v_mfma_f32_16x16x32_bf16 v[102:105], v[154:157], v[106:109], v[102:105]
	ds_read_b128 v[154:157], v138 offset:0x2440
	ds_read_b128 v[158:161], v138 offset:0x2d00
	v_mfma_f32_16x16x32_bf16 v[90:93], v[174:177], v[110:113], v[90:93]
	v_mfma_f32_16x16x32_bf16 v[98:101], v[162:165], v[106:109], v[98:101]
	ds_read_b128 v[162:165], v138 offset:0x2d40
	ds_read_b128 v[166:169], v138 offset:0x3600
	v_mfma_f32_16x16x32_bf16 v[94:97], v[170:173], v[106:109], v[94:97]
	ds_read_b128 v[170:173], v138 offset:0x3640
	ds_read_b128 v[174:177], v138 offset:0x3f00
	v_mfma_f32_16x16x32_bf16 v[90:93], v[178:181], v[106:109], v[90:93]
	ds_read_b128 v[178:181], v138 offset:0x3f40
	ds_read_b128 v[192:195], v139 offset:0x100
	ds_read_b128 v[196:199], v139 offset:0x140
	ds_read_b128 v[200:203], v139 offset:0x180
	ds_read_b128 v[204:207], v139 offset:0x1c0
	s_waitcnt lgkmcnt(0)
	s_nop 0
	v_mul_f32_e64 v76, v76, v194
	v_mul_f32_e64 v77, v77, v195
	v_pk_mul_f32 v[74:75], v[74:75], v[192:193]
	v_pk_mul_f32 v[68:69], v[68:69], v[198:199]
	v_mfma_f32_16x16x32_bf16 v[74:77], v[142:145], v[110:113], v[74:77]
	v_mov_b32_e32 v142, v64
	v_lshlrev_b32_e32 v64, 3, v140
	v_lshl_add_u64 v[140:141], s[8:9], 0, v[64:65]
	v_add_u32_e32 v144, s26, v142
	v_sub_u32_e32 v145, s25, v142
	v_cvt_pk_bf16_f32 v126, v126, v127
	v_cvt_pk_bf16_f32 v127, v128, v129
	v_subrev_u32_e32 v128, 51, v144
	v_add_u32_e32 v143, 0x7ff, v145
	v_cndmask_b32_e32 v128, v143, v128, vcc
	v_add_u32_e32 v128, s7, v128
	v_ashrrev_i32_e32 v129, 31, v128
	v_lshlrev_b64 v[128:129], 12, v[128:129]
	v_lshl_add_u64 v[128:129], v[140:141], 0, v[128:129]
	global_store_dwordx2 v[128:129], v[126:127], off
	v_cvt_pk_bf16_f32 v122, v122, v123
	v_cvt_pk_bf16_f32 v123, v124, v125
	v_subrev_u32_e32 v124, 35, v144
	v_add_u32_e32 v143, 0x7ef, v145
	v_cndmask_b32_e32 v124, v143, v124, vcc
	v_add_u32_e32 v124, s7, v124
	v_ashrrev_i32_e32 v125, 31, v124
	v_lshlrev_b64 v[124:125], 12, v[124:125]
	v_lshl_add_u64 v[124:125], v[140:141], 0, v[124:125]
	global_store_dwordx2 v[124:125], v[122:123], off
	v_cvt_pk_bf16_f32 v118, v118, v119
	v_cvt_pk_bf16_f32 v119, v120, v121
	v_subrev_u32_e32 v120, 19, v144
	v_add_u32_e32 v143, 0x7df, v145
	v_cndmask_b32_e32 v120, v143, v120, vcc
	v_add_u32_e32 v120, s7, v120
	v_ashrrev_i32_e32 v121, 31, v120
	v_lshlrev_b64 v[120:121], 12, v[120:121]
	v_lshl_add_u64 v[120:121], v[140:141], 0, v[120:121]
	global_store_dwordx2 v[120:121], v[118:119], off
	v_cvt_pk_bf16_f32 v114, v114, v115
	v_cvt_pk_bf16_f32 v115, v116, v117
	v_subrev_u32_e32 v116, 3, v144
	v_add_u32_e32 v143, 0x7cf, v145
	v_cndmask_b32_e32 v116, v143, v116, vcc
	v_add_u32_e32 v116, s7, v116
	v_ashrrev_i32_e32 v117, 31, v116
	v_lshlrev_b64 v[116:117], 12, v[116:117]
	v_lshl_add_u64 v[116:117], v[140:141], 0, v[116:117]
	global_store_dwordx2 v[116:117], v[114:115], off
	ds_read_b128 v[114:117], v138 offset:0x4800
	ds_read_b128 v[118:121], v138 offset:0x4840
	ds_read_b128 v[122:125], v138 offset:0x5100
	v_pk_mul_f32 v[66:67], v[66:67], v[196:197]
	ds_read_b128 v[126:129], v138 offset:0x5140
	ds_read_b128 v[140:143], v138 offset:0x5a00
	v_pk_mul_f32 v[62:63], v[62:63], v[202:203]
	v_pk_mul_f32 v[60:61], v[60:61], v[200:201]
	v_mfma_f32_16x16x32_bf16 v[66:69], v[158:161], v[110:113], v[66:69]
	ds_read_b128 v[144:147], v138 offset:0x5a40
	v_mul_f32_e64 v58, v58, v206
	v_mul_f32_e64 v59, v59, v207
	v_pk_mul_f32 v[56:57], v[56:57], v[204:205]
	v_mfma_f32_16x16x32_bf16 v[60:63], v[166:169], v[110:113], v[60:63]
	v_mfma_f32_16x16x32_bf16 v[74:77], v[154:157], v[106:109], v[74:77]
	ds_read_b128 v[154:157], v138 offset:0x6300
	ds_read_b128 v[158:161], v138 offset:0x6340
	v_mfma_f32_16x16x32_bf16 v[56:59], v[174:177], v[110:113], v[56:59]
	v_mfma_f32_16x16x32_bf16 v[66:69], v[162:165], v[106:109], v[66:69]
	ds_read_b128 v[162:165], v139 offset:0x200
	ds_read_b128 v[166:169], v139 offset:0x240
	v_mfma_f32_16x16x32_bf16 v[60:63], v[170:173], v[106:109], v[60:63]
	ds_read_b128 v[170:173], v139 offset:0x280
	ds_read_b128 v[174:177], v139 offset:0x2c0
	s_waitcnt lgkmcnt(0)
	v_mfma_f32_16x16x32_bf16 v[56:59], v[178:181], v[106:109], v[56:59]
	v_mul_f32_e64 v88, v88, v164
	v_mul_f32_e64 v89, v89, v165
	v_pk_mul_f32 v[86:87], v[86:87], v[162:163]
	v_pk_mul_f32 v[84:85], v[84:85], v[168:169]
	v_pk_mul_f32 v[82:83], v[82:83], v[166:167]
	v_mfma_f32_16x16x32_bf16 v[86:89], v[114:117], v[110:113], v[86:89]
	v_mul_f32_e64 v80, v80, v172
	v_mul_f32_e64 v81, v81, v173
	v_pk_mul_f32 v[78:79], v[78:79], v[170:171]
	ds_read_b128 v[114:117], v138 offset:0x6c00
	v_mfma_f32_16x16x32_bf16 v[82:85], v[122:125], v[110:113], v[82:85]
	v_mul_f32_e64 v72, v72, v176
	v_mul_f32_e64 v73, v73, v177
	v_pk_mul_f32 v[70:71], v[70:71], v[174:175]
	v_mfma_f32_16x16x32_bf16 v[78:81], v[140:143], v[110:113], v[78:81]
	v_mfma_f32_16x16x32_bf16 v[86:89], v[118:121], v[106:109], v[86:89]
	ds_read_b128 v[118:121], v138 offset:0x6c40
	ds_read_b128 v[122:125], v138 offset:0x7500
	v_mfma_f32_16x16x32_bf16 v[70:73], v[154:157], v[110:113], v[70:73]
	v_mfma_f32_16x16x32_bf16 v[82:85], v[126:129], v[106:109], v[82:85]
	ds_read_b128 v[126:129], v138 offset:0x7540
	ds_read_b128 v[140:143], v138 offset:0x7e00
	v_mfma_f32_16x16x32_bf16 v[78:81], v[144:147], v[106:109], v[78:81]
	ds_read_b128 v[144:147], v138 offset:0x7e40
	ds_read_b128 v[154:157], v138 offset:0x8700
	v_mfma_f32_16x16x32_bf16 v[70:73], v[158:161], v[106:109], v[70:73]
	ds_read_b128 v[158:161], v138 offset:0x8740
	ds_read_b128 v[162:165], v139 offset:0x300
	ds_read_b128 v[166:169], v139 offset:0x340
	ds_read_b128 v[170:173], v139 offset:0x380
	ds_read_b128 v[174:177], v139 offset:0x3c0
	s_waitcnt lgkmcnt(0)
	s_nop 0
	v_mul_f32_e64 v50, v50, v164
	v_mul_f32_e64 v51, v51, v165
	v_pk_mul_f32 v[48:49], v[48:49], v[162:163]
	v_pk_mul_f32 v[46:47], v[46:47], v[168:169]
	v_pk_mul_f32 v[44:45], v[44:45], v[166:167]
	v_pk_mul_f32 v[38:39], v[38:39], v[172:173]
	v_pk_mul_f32 v[36:37], v[36:37], v[170:171]
	v_pk_mul_f32 v[54:55], v[54:55], v[176:177]
	v_pk_mul_f32 v[52:53], v[52:53], v[174:175]
	v_mfma_f32_16x16x32_bf16 v[48:51], v[114:117], v[110:113], v[48:51]
	s_add_i32 s26, s26, 64
	s_sub_i32 s25, s25, 64
	s_add_i32 s24, s24, 1
	v_mfma_f32_16x16x32_bf16 v[44:47], v[122:125], v[110:113], v[44:47]
	s_cmpk_lg_i32 s26, 0x833
	v_mfma_f32_16x16x32_bf16 v[36:39], v[140:143], v[110:113], v[36:39]
	v_mfma_f32_16x16x32_bf16 v[52:55], v[154:157], v[110:113], v[52:55]
	v_mfma_f32_16x16x32_bf16 v[48:51], v[118:121], v[106:109], v[48:51]
	v_mfma_f32_16x16x32_bf16 v[44:47], v[126:129], v[106:109], v[44:47]
	v_mfma_f32_16x16x32_bf16 v[36:39], v[144:147], v[106:109], v[36:39]
	v_mfma_f32_16x16x32_bf16 v[52:55], v[158:161], v[106:109], v[52:55]
	s_cbranch_scc0 .LBB0_241
.LBB0_244:
	v_mov_b32_e32 v64, 0
	s_waitcnt lgkmcnt(0)
	s_barrier
	v_add_u32_e32 v108, v64, v190
	v_lshlrev_b32_e32 v106, 4, v108
	v_and_b32_e32 v64, 0x1f0, v106
	v_add_u32_e32 v110, 0, v64
	v_ashrrev_i32_e32 v64, 5, v108
	v_and_b32_e32 v107, 0x70, v106
	v_bfe_u32 v208, v108, 3, 4
	v_add_u32_e32 v208, 4, v208
	v_lshlrev_b32_e32 v208, 1, v208
	v_and_b32_e32 v208, 16, v208
	v_xor_b32_e32 v107, v107, v208
	v_mad_u64_u32 v[114:115], s[10:11], v64, s37, v[110:111]
	v_ashrrev_i32_e32 v64, 3, v108
	v_add_u32_e32 v112, s36, v107
	s_waitcnt vmcnt(4)
	ds_write_b128 v114, v[0:3]
	v_mul_lo_u32 v2, v64, s38
	v_add_u32_e32 v0, v112, v2
	v_add_u32_e32 v3, 0x200, v108
	s_waitcnt vmcnt(16)
	ds_write_b128 v0, v[4:7]
	v_ashrrev_i32_e32 v0, 5, v3
	v_mad_u64_u32 v[0:1], s[10:11], v0, s37, v[110:111]
	s_waitcnt vmcnt(15)
	ds_write_b128 v0, v[8:11]
	v_lshrrev_b32_e32 v0, 3, v3
	v_mad_u64_u32 v[0:1], s[10:11], v0, s38, v[112:113]
	v_add_u32_e32 v3, 0x400, v108
	s_waitcnt vmcnt(14)
	ds_write_b128 v0, v[12:15]
	v_ashrrev_i32_e32 v0, 5, v3
	v_mad_u64_u32 v[0:1], s[10:11], v0, s37, v[110:111]
	s_waitcnt vmcnt(13)
	ds_write_b128 v0, v[16:19]
	v_lshrrev_b32_e32 v0, 3, v3
	v_mad_u64_u32 v[0:1], s[10:11], v0, s38, v[112:113]
	v_add_u32_e32 v3, 0x600, v108
	s_waitcnt vmcnt(12)
	ds_write_b128 v0, v[20:23]
	v_ashrrev_i32_e32 v0, 5, v3
	v_mad_u64_u32 v[0:1], s[10:11], v0, s37, v[110:111]
	s_waitcnt vmcnt(11)
	ds_write_b128 v0, v[24:27]
	v_lshrrev_b32_e32 v0, 3, v3
	v_mad_u64_u32 v[0:1], s[10:11], v0, s38, v[112:113]
	s_add_i32 s27, 0, 0x1e000
	s_waitcnt vmcnt(10)
	ds_write_b128 v0, v[28:31]
	v_add3_u32 v0, s27, v2, v107
	v_cmp_gt_i32_e64 s[62:63], 64, v108
	v_ashrrev_i32_e32 v107, 31, v106
	s_waitcnt vmcnt(9)
	ds_write_b128 v0, v[32:35]
	s_and_saveexec_b64 s[10:11], s[62:63]
	s_cbranch_execz .LBB0_243
	v_add_u32_e32 v0, 0, v106
	v_add_u32_e32 v0, 0x22400, v0
	s_waitcnt vmcnt(8)
	ds_write_b128 v0, v[40:43]
	s_branch .LBB0_243
